# v72 + FF-IN activation tile stores with the nt hint only (no sc1 write-through)
# speedup vs baseline: 1.0037x; 1.0022x over previous
;     __device__ __forceinline__ void operator()(const f32x4 (&acc)[2][2][4][2], const Unit& u, int wr, int wc, int fr, int fq) const {
;     ...
;             for (int m = 0; m < 4; ++m) {
;                 const int row = row0 + ai * HALF + m * 16; const float rs = rsv[m];
;                 const f32x4 ca = acc[ai][0][m][0] * rs, cb_ = acc[ai][0][m][1] * rs;
;                 f32x4 aa = w2a * ca + ba, ab = w2b * cb_ + bb;
; #pragma unroll
;                 for (int c = 0; c < 4; ++c) { aa[c] = __builtin_fmaf(w1a[c], dpp_shr1(ca[c]), aa[c]); ab[c] = __builtin_fmaf(w1b[c], dpp_shr1(cb_[c]), ab[c]);
;                     aa[c] = __builtin_fmaf(w0a[c], dpp_shr2(ca[c]), aa[c]); ab[c] = __builtin_fmaf(w0b[c], dpp_shr2(cb_[c]), ab[c]); }
;                 if (m == 0) {
;                     if (ai == 1 || wr == 1) { const int sw = ((ai == 1 && wr == 0) ? 4 : 0) + wc, sai = (ai == 1 && wr == 1) ? 1 : 0;
;                         const PG8_LAS f32x4* xp = (const PG8_LAS f32x4*)(X + ((sw * 2 + sai) * 2) * 32 + fq * 8); const f32x4 h0a = xp[0], h0b = xp[1], h1a = xp[8], h1b = xp[9];
;                         aa += w1a * (h1a * m0) + w0a * (h0a * m0 + h1a * m1); ab += w1b * (h1b * m0) + w0b * (h0b * m0 + h1b * m1); }
;                 } else {
; #pragma unroll
;                     for (int c = 0; c < 4; ++c) { aa[c] = __builtin_fmaf(w1a[c], dpp_shl15(pa[c]), aa[c]); ab[c] = __builtin_fmaf(w1b[c], dpp_shl15(pb[c]), ab[c]);
;                         aa[c] = __builtin_fmaf(w0a[c], dpp_shl14(pa[c]), aa[c]); ab[c] = __builtin_fmaf(w0b[c], dpp_shl14(pb[c]), ab[c]); }
;                 }
;                 const f32x4 ga = acc[ai][1][m][0] * rs, gb = acc[ai][1][m][1] * rs;
;                 f32x4 ea = aa * -1.4426950408889634f, eb = ab * -1.4426950408889634f;
; #pragma unroll
;                 for (int c = 0; c < 4; ++c) { ea[c] = __builtin_amdgcn_exp2f(ea[c]); eb[c] = __builtin_amdgcn_exp2f(eb[c]); }
;                 ea = ea + 1.0f; eb = eb + 1.0f;
; #pragma unroll
;                 for (int c = 0; c < 4; ++c) { ea[c] = __builtin_amdgcn_rcpf(ea[c]); eb[c] = __builtin_amdgcn_rcpf(eb[c]); }
;                 const f32x4 oa = (aa * ga) * ea, ob = (ab * gb) * eb;
;                 u32x4 w; w.x = cvt_pk_bf16(oa[0], oa[1]); w.y = cvt_pk_bf16(oa[2], oa[3]); w.z = cvt_pk_bf16(ob[0], ob[1]); w.w = cvt_pk_bf16(ob[2], ob[3]);
;                 *(u32x4*)(act + (size_t)row * FF + col) = w;
.Lffin_nopark:
	s_or_b64 exec, exec, s[46:47]
	v_pk_mul_f32 v[244:245], v[236:237], s[92:93] op_sel_hi:[1,0]
	v_pk_mul_f32 v[246:247], v[238:239], s[92:93] op_sel_hi:[1,0]
	v_pk_mul_f32 v[248:249], v[240:241], s[92:93] op_sel_hi:[1,0]
	v_pk_mul_f32 v[250:251], v[242:243], s[92:93] op_sel_hi:[1,0]
	v_exp_f32_e32 v244, v244
	v_exp_f32_e32 v245, v245
	v_exp_f32_e32 v246, v246
	v_exp_f32_e32 v247, v247
	v_exp_f32_e32 v248, v248
	v_exp_f32_e32 v249, v249
	v_exp_f32_e32 v250, v250
	v_exp_f32_e32 v251, v251
	v_pk_mul_f32 v[236:237], v[236:237], v[150:151]
	v_pk_mul_f32 v[238:239], v[238:239], v[152:153]
	v_pk_mul_f32 v[240:241], v[240:241], v[146:147]
	v_pk_mul_f32 v[242:243], v[242:243], v[148:149]
	v_pk_add_f32 v[244:245], v[244:245], 1.0 op_sel_hi:[1,0]
	v_pk_add_f32 v[246:247], v[246:247], 1.0 op_sel_hi:[1,0]
	v_pk_add_f32 v[248:249], v[248:249], 1.0 op_sel_hi:[1,0]
	v_pk_add_f32 v[250:251], v[250:251], 1.0 op_sel_hi:[1,0]
	v_rcp_f32_e32 v244, v244
	v_rcp_f32_e32 v245, v245
	v_rcp_f32_e32 v246, v246
	v_rcp_f32_e32 v247, v247
	v_rcp_f32_e32 v248, v248
	v_rcp_f32_e32 v249, v249
	v_rcp_f32_e32 v250, v250
	v_rcp_f32_e32 v251, v251
	s_nop 0
	v_pk_mul_f32 v[236:237], v[236:237], v[244:245]
	v_pk_mul_f32 v[238:239], v[238:239], v[246:247]
	v_pk_mul_f32 v[240:241], v[240:241], v[248:249]
	v_pk_mul_f32 v[242:243], v[242:243], v[250:251]
	v_cvt_pk_bf16_f32 v216, v236, v237
	v_cvt_pk_bf16_f32 v217, v238, v239
	v_cvt_pk_bf16_f32 v218, v240, v241
	v_cvt_pk_bf16_f32 v219, v242, v243
	global_store_dwordx4 v[220:221], v[216:219], off nt
	v_lshl_add_u64 v[220:221], v[220:221], 0, s[100:101]
	v_pk_mul_f32 v[142:143], v[142:143], v[164:165] op_sel_hi:[1,0]
	v_pk_mul_f32 v[144:145], v[144:145], v[164:165] op_sel_hi:[1,0]
	v_pk_mul_f32 v[138:139], v[138:139], v[164:165] op_sel_hi:[1,0]
	v_pk_mul_f32 v[140:141], v[140:141], v[164:165] op_sel_hi:[1,0]
	v_pk_fma_f32 v[236:237], v[122:123], v[142:143], v[130:131]
	v_pk_fma_f32 v[238:239], v[124:125], v[144:145], v[132:133]
	v_pk_fma_f32 v[240:241], v[126:127], v[138:139], v[134:135]
	v_pk_fma_f32 v[242:243], v[128:129], v[140:141], v[136:137]
	v_pk_mul_f32 v[102:103], v[102:103], v[164:165] op_sel_hi:[1,0]
	v_pk_mul_f32 v[104:105], v[104:105], v[164:165] op_sel_hi:[1,0]
	v_pk_mul_f32 v[98:99], v[98:99], v[164:165] op_sel_hi:[1,0]
	v_pk_mul_f32 v[100:101], v[100:101], v[164:165] op_sel_hi:[1,0]
	v_fmac_f32_dpp v236, v142, v114 row_shr:1 row_mask:0xf bank_mask:0xf bound_ctrl:1
	v_fmac_f32_dpp v237, v143, v115 row_shr:1 row_mask:0xf bank_mask:0xf bound_ctrl:1
	v_fmac_f32_dpp v238, v144, v116 row_shr:1 row_mask:0xf bank_mask:0xf bound_ctrl:1
	v_fmac_f32_dpp v239, v145, v117 row_shr:1 row_mask:0xf bank_mask:0xf bound_ctrl:1
	v_fmac_f32_dpp v240, v138, v118 row_shr:1 row_mask:0xf bank_mask:0xf bound_ctrl:1
	v_fmac_f32_dpp v241, v139, v119 row_shr:1 row_mask:0xf bank_mask:0xf bound_ctrl:1
	v_fmac_f32_dpp v242, v140, v120 row_shr:1 row_mask:0xf bank_mask:0xf bound_ctrl:1
	v_fmac_f32_dpp v243, v141, v121 row_shr:1 row_mask:0xf bank_mask:0xf bound_ctrl:1
	v_fmac_f32_dpp v236, v142, v106 row_shr:2 row_mask:0xf bank_mask:0xf bound_ctrl:1
	v_fmac_f32_dpp v237, v143, v107 row_shr:2 row_mask:0xf bank_mask:0xf bound_ctrl:1
	v_fmac_f32_dpp v238, v144, v108 row_shr:2 row_mask:0xf bank_mask:0xf bound_ctrl:1
	v_fmac_f32_dpp v239, v145, v109 row_shr:2 row_mask:0xf bank_mask:0xf bound_ctrl:1
	v_fmac_f32_dpp v240, v138, v110 row_shr:2 row_mask:0xf bank_mask:0xf bound_ctrl:1
	v_fmac_f32_dpp v241, v139, v111 row_shr:2 row_mask:0xf bank_mask:0xf bound_ctrl:1
	v_fmac_f32_dpp v242, v140, v112 row_shr:2 row_mask:0xf bank_mask:0xf bound_ctrl:1
	v_fmac_f32_dpp v243, v141, v113 row_shr:2 row_mask:0xf bank_mask:0xf bound_ctrl:1
	v_fmac_f32_dpp v236, v158, v114 row_shl:15 row_mask:0xf bank_mask:0xf bound_ctrl:1
	v_fmac_f32_dpp v237, v159, v115 row_shl:15 row_mask:0xf bank_mask:0xf bound_ctrl:1
	v_fmac_f32_dpp v238, v160, v116 row_shl:15 row_mask:0xf bank_mask:0xf bound_ctrl:1
	v_fmac_f32_dpp v239, v161, v117 row_shl:15 row_mask:0xf bank_mask:0xf bound_ctrl:1
	v_fmac_f32_dpp v240, v154, v118 row_shl:15 row_mask:0xf bank_mask:0xf bound_ctrl:1
	v_fmac_f32_dpp v241, v155, v119 row_shl:15 row_mask:0xf bank_mask:0xf bound_ctrl:1
	v_fmac_f32_dpp v242, v156, v120 row_shl:15 row_mask:0xf bank_mask:0xf bound_ctrl:1
	v_fmac_f32_dpp v243, v157, v121 row_shl:15 row_mask:0xf bank_mask:0xf bound_ctrl:1
	v_fmac_f32_dpp v236, v158, v106 row_shl:14 row_mask:0xf bank_mask:0xf bound_ctrl:1
	v_fmac_f32_dpp v237, v159, v107 row_shl:14 row_mask:0xf bank_mask:0xf bound_ctrl:1
	v_fmac_f32_dpp v238, v160, v108 row_shl:14 row_mask:0xf bank_mask:0xf bound_ctrl:1
	v_fmac_f32_dpp v239, v161, v109 row_shl:14 row_mask:0xf bank_mask:0xf bound_ctrl:1
	v_fmac_f32_dpp v240, v154, v110 row_shl:14 row_mask:0xf bank_mask:0xf bound_ctrl:1
	v_fmac_f32_dpp v241, v155, v111 row_shl:14 row_mask:0xf bank_mask:0xf bound_ctrl:1
	v_fmac_f32_dpp v242, v156, v112 row_shl:14 row_mask:0xf bank_mask:0xf bound_ctrl:1
	v_fmac_f32_dpp v243, v157, v113 row_shl:14 row_mask:0xf bank_mask:0xf bound_ctrl:1
	v_pk_mul_f32 v[244:245], v[236:237], s[92:93] op_sel_hi:[1,0]
	v_pk_mul_f32 v[246:247], v[238:239], s[92:93] op_sel_hi:[1,0]
	v_pk_mul_f32 v[248:249], v[240:241], s[92:93] op_sel_hi:[1,0]
	v_pk_mul_f32 v[250:251], v[242:243], s[92:93] op_sel_hi:[1,0]
	v_exp_f32_e32 v244, v244
	v_exp_f32_e32 v245, v245
	v_exp_f32_e32 v246, v246
	v_exp_f32_e32 v247, v247
	v_exp_f32_e32 v248, v248
	v_exp_f32_e32 v249, v249
	v_exp_f32_e32 v250, v250
	v_exp_f32_e32 v251, v251
	v_pk_mul_f32 v[236:237], v[236:237], v[102:103]
	v_pk_mul_f32 v[238:239], v[238:239], v[104:105]
	v_pk_mul_f32 v[240:241], v[240:241], v[98:99]
;     __device__ __forceinline__ void operator()(const f32x4 (&acc)[2][2][4][2], const Unit& u, int wr, int wc, int fr, int fq) const {
;     ...
;             for (int m = 0; m < 4; ++m) {
;                 const int row = row0 + ai * HALF + m * 16; const float rs = rsv[m];
;                 const f32x4 ca = acc[ai][0][m][0] * rs, cb_ = acc[ai][0][m][1] * rs;
;                 f32x4 aa = w2a * ca + ba, ab = w2b * cb_ + bb;
; #pragma unroll
;                 for (int c = 0; c < 4; ++c) { aa[c] = __builtin_fmaf(w1a[c], dpp_shr1(ca[c]), aa[c]); ab[c] = __builtin_fmaf(w1b[c], dpp_shr1(cb_[c]), ab[c]);
;                     aa[c] = __builtin_fmaf(w0a[c], dpp_shr2(ca[c]), aa[c]); ab[c] = __builtin_fmaf(w0b[c], dpp_shr2(cb_[c]), ab[c]); }
;                 if (m == 0) {
;                     if (ai == 1 || wr == 1) { const int sw = ((ai == 1 && wr == 0) ? 4 : 0) + wc, sai = (ai == 1 && wr == 1) ? 1 : 0;
;                         const PG8_LAS f32x4* xp = (const PG8_LAS f32x4*)(X + ((sw * 2 + sai) * 2) * 32 + fq * 8); const f32x4 h0a = xp[0], h0b = xp[1], h1a = xp[8], h1b = xp[9];
;                         aa += w1a * (h1a * m0) + w0a * (h0a * m0 + h1a * m1); ab += w1b * (h1b * m0) + w0b * (h0b * m0 + h1b * m1); }
;                 } else {
; #pragma unroll
;                     for (int c = 0; c < 4; ++c) { aa[c] = __builtin_fmaf(w1a[c], dpp_shl15(pa[c]), aa[c]); ab[c] = __builtin_fmaf(w1b[c], dpp_shl15(pb[c]), ab[c]);
;                         aa[c] = __builtin_fmaf(w0a[c], dpp_shl14(pa[c]), aa[c]); ab[c] = __builtin_fmaf(w0b[c], dpp_shl14(pb[c]), ab[c]); }
;                 }
;                 const f32x4 ga = acc[ai][1][m][0] * rs, gb = acc[ai][1][m][1] * rs;
;                 f32x4 ea = aa * -1.4426950408889634f, eb = ab * -1.4426950408889634f;
; #pragma unroll
;                 for (int c = 0; c < 4; ++c) { ea[c] = __builtin_amdgcn_exp2f(ea[c]); eb[c] = __builtin_amdgcn_exp2f(eb[c]); }
;                 ea = ea + 1.0f; eb = eb + 1.0f;
; #pragma unroll
;                 for (int c = 0; c < 4; ++c) { ea[c] = __builtin_amdgcn_rcpf(ea[c]); eb[c] = __builtin_amdgcn_rcpf(eb[c]); }
;                 const f32x4 oa = (aa * ga) * ea, ob = (ab * gb) * eb;
;                 u32x4 w; w.x = cvt_pk_bf16(oa[0], oa[1]); w.y = cvt_pk_bf16(oa[2], oa[3]); w.z = cvt_pk_bf16(ob[0], ob[1]); w.w = cvt_pk_bf16(ob[2], ob[3]);
;                 *(u32x4*)(act + (size_t)row * FF + col) = w;
	v_pk_mul_f32 v[242:243], v[242:243], v[100:101]
	v_pk_add_f32 v[244:245], v[244:245], 1.0 op_sel_hi:[1,0]
	v_pk_add_f32 v[246:247], v[246:247], 1.0 op_sel_hi:[1,0]
	v_pk_add_f32 v[248:249], v[248:249], 1.0 op_sel_hi:[1,0]
	v_pk_add_f32 v[250:251], v[250:251], 1.0 op_sel_hi:[1,0]
	v_rcp_f32_e32 v244, v244
	v_rcp_f32_e32 v245, v245
	v_rcp_f32_e32 v246, v246
	v_rcp_f32_e32 v247, v247
	v_rcp_f32_e32 v248, v248
	v_rcp_f32_e32 v249, v249
	v_rcp_f32_e32 v250, v250
	v_rcp_f32_e32 v251, v251
	s_nop 0
	v_pk_mul_f32 v[236:237], v[236:237], v[244:245]
	v_pk_mul_f32 v[238:239], v[238:239], v[246:247]
	v_pk_mul_f32 v[240:241], v[240:241], v[248:249]
	v_pk_mul_f32 v[242:243], v[242:243], v[250:251]
	v_cvt_pk_bf16_f32 v216, v236, v237
	v_cvt_pk_bf16_f32 v217, v238, v239
	v_cvt_pk_bf16_f32 v218, v240, v241
	v_cvt_pk_bf16_f32 v219, v242, v243
	global_store_dwordx4 v[220:221], v[216:219], off nt
	v_lshl_add_u64 v[220:221], v[220:221], 0, s[100:101]
	v_pk_mul_f32 v[94:95], v[94:95], v[166:167] op_sel_hi:[1,0]
	v_pk_mul_f32 v[96:97], v[96:97], v[166:167] op_sel_hi:[1,0]
	v_pk_mul_f32 v[90:91], v[90:91], v[166:167] op_sel_hi:[1,0]
	v_pk_mul_f32 v[92:93], v[92:93], v[166:167] op_sel_hi:[1,0]
	v_pk_fma_f32 v[236:237], v[122:123], v[94:95], v[130:131]
	v_pk_fma_f32 v[238:239], v[124:125], v[96:97], v[132:133]
	v_pk_fma_f32 v[240:241], v[126:127], v[90:91], v[134:135]
	v_pk_fma_f32 v[242:243], v[128:129], v[92:93], v[136:137]
	v_pk_mul_f32 v[86:87], v[86:87], v[166:167] op_sel_hi:[1,0]
	v_pk_mul_f32 v[88:89], v[88:89], v[166:167] op_sel_hi:[1,0]
	v_pk_mul_f32 v[82:83], v[82:83], v[166:167] op_sel_hi:[1,0]
	v_pk_mul_f32 v[84:85], v[84:85], v[166:167] op_sel_hi:[1,0]
	v_fmac_f32_dpp v236, v94, v114 row_shr:1 row_mask:0xf bank_mask:0xf bound_ctrl:1
	v_fmac_f32_dpp v237, v95, v115 row_shr:1 row_mask:0xf bank_mask:0xf bound_ctrl:1
	v_fmac_f32_dpp v238, v96, v116 row_shr:1 row_mask:0xf bank_mask:0xf bound_ctrl:1
	v_fmac_f32_dpp v239, v97, v117 row_shr:1 row_mask:0xf bank_mask:0xf bound_ctrl:1
	v_fmac_f32_dpp v240, v90, v118 row_shr:1 row_mask:0xf bank_mask:0xf bound_ctrl:1
	v_fmac_f32_dpp v241, v91, v119 row_shr:1 row_mask:0xf bank_mask:0xf bound_ctrl:1
	v_fmac_f32_dpp v242, v92, v120 row_shr:1 row_mask:0xf bank_mask:0xf bound_ctrl:1
	v_fmac_f32_dpp v243, v93, v121 row_shr:1 row_mask:0xf bank_mask:0xf bound_ctrl:1
	v_fmac_f32_dpp v236, v94, v106 row_shr:2 row_mask:0xf bank_mask:0xf bound_ctrl:1
	v_fmac_f32_dpp v237, v95, v107 row_shr:2 row_mask:0xf bank_mask:0xf bound_ctrl:1
	v_fmac_f32_dpp v238, v96, v108 row_shr:2 row_mask:0xf bank_mask:0xf bound_ctrl:1
	v_fmac_f32_dpp v239, v97, v109 row_shr:2 row_mask:0xf bank_mask:0xf bound_ctrl:1
	v_fmac_f32_dpp v240, v90, v110 row_shr:2 row_mask:0xf bank_mask:0xf bound_ctrl:1
	v_fmac_f32_dpp v241, v91, v111 row_shr:2 row_mask:0xf bank_mask:0xf bound_ctrl:1
	v_fmac_f32_dpp v242, v92, v112 row_shr:2 row_mask:0xf bank_mask:0xf bound_ctrl:1
	v_fmac_f32_dpp v243, v93, v113 row_shr:2 row_mask:0xf bank_mask:0xf bound_ctrl:1
	v_fmac_f32_dpp v236, v142, v114 row_shl:15 row_mask:0xf bank_mask:0xf bound_ctrl:1
	v_fmac_f32_dpp v237, v143, v115 row_shl:15 row_mask:0xf bank_mask:0xf bound_ctrl:1
	v_fmac_f32_dpp v238, v144, v116 row_shl:15 row_mask:0xf bank_mask:0xf bound_ctrl:1
	v_fmac_f32_dpp v239, v145, v117 row_shl:15 row_mask:0xf bank_mask:0xf bound_ctrl:1
	v_fmac_f32_dpp v240, v138, v118 row_shl:15 row_mask:0xf bank_mask:0xf bound_ctrl:1
	v_fmac_f32_dpp v241, v139, v119 row_shl:15 row_mask:0xf bank_mask:0xf bound_ctrl:1
	v_fmac_f32_dpp v242, v140, v120 row_shl:15 row_mask:0xf bank_mask:0xf bound_ctrl:1
	v_fmac_f32_dpp v243, v141, v121 row_shl:15 row_mask:0xf bank_mask:0xf bound_ctrl:1
	v_fmac_f32_dpp v236, v142, v106 row_shl:14 row_mask:0xf bank_mask:0xf bound_ctrl:1
	v_fmac_f32_dpp v237, v143, v107 row_shl:14 row_mask:0xf bank_mask:0xf bound_ctrl:1
	v_fmac_f32_dpp v238, v144, v108 row_shl:14 row_mask:0xf bank_mask:0xf bound_ctrl:1
	v_fmac_f32_dpp v239, v145, v109 row_shl:14 row_mask:0xf bank_mask:0xf bound_ctrl:1
	v_fmac_f32_dpp v240, v138, v110 row_shl:14 row_mask:0xf bank_mask:0xf bound_ctrl:1
	v_fmac_f32_dpp v241, v139, v111 row_shl:14 row_mask:0xf bank_mask:0xf bound_ctrl:1
	v_fmac_f32_dpp v242, v140, v112 row_shl:14 row_mask:0xf bank_mask:0xf bound_ctrl:1
	v_fmac_f32_dpp v243, v141, v113 row_shl:14 row_mask:0xf bank_mask:0xf bound_ctrl:1
	v_pk_mul_f32 v[244:245], v[236:237], s[92:93] op_sel_hi:[1,0]
	v_pk_mul_f32 v[246:247], v[238:239], s[92:93] op_sel_hi:[1,0]
	v_pk_mul_f32 v[248:249], v[240:241], s[92:93] op_sel_hi:[1,0]
	v_pk_mul_f32 v[250:251], v[242:243], s[92:93] op_sel_hi:[1,0]
	v_exp_f32_e32 v244, v244
	v_exp_f32_e32 v245, v245
	v_exp_f32_e32 v246, v246
	v_exp_f32_e32 v247, v247
	v_exp_f32_e32 v248, v248
	v_exp_f32_e32 v249, v249
	v_exp_f32_e32 v250, v250
	v_exp_f32_e32 v251, v251
	v_pk_mul_f32 v[236:237], v[236:237], v[86:87]
	v_pk_mul_f32 v[238:239], v[238:239], v[88:89]
	v_pk_mul_f32 v[240:241], v[240:241], v[82:83]
	v_pk_mul_f32 v[242:243], v[242:243], v[84:85]
	v_pk_add_f32 v[244:245], v[244:245], 1.0 op_sel_hi:[1,0]
	v_pk_add_f32 v[246:247], v[246:247], 1.0 op_sel_hi:[1,0]
	v_pk_add_f32 v[248:249], v[248:249], 1.0 op_sel_hi:[1,0]
	v_pk_add_f32 v[250:251], v[250:251], 1.0 op_sel_hi:[1,0]
	v_rcp_f32_e32 v244, v244
	v_rcp_f32_e32 v245, v245
	v_rcp_f32_e32 v246, v246
	v_rcp_f32_e32 v247, v247
	v_rcp_f32_e32 v248, v248
	v_rcp_f32_e32 v249, v249
	v_rcp_f32_e32 v250, v250
	v_rcp_f32_e32 v251, v251
	s_nop 0
	v_pk_mul_f32 v[236:237], v[236:237], v[244:245]
	v_pk_mul_f32 v[238:239], v[238:239], v[246:247]
	v_pk_mul_f32 v[240:241], v[240:241], v[248:249]
	v_pk_mul_f32 v[242:243], v[242:243], v[250:251]
	v_cvt_pk_bf16_f32 v216, v236, v237
;     __device__ __forceinline__ void operator()(const f32x4 (&acc)[2][2][4][2], const Unit& u, int wr, int wc, int fr, int fq) const {
;     ...
;             for (int m = 0; m < 4; ++m) {
;                 const int row = row0 + ai * HALF + m * 16; const float rs = rsv[m];
;                 const f32x4 ca = acc[ai][0][m][0] * rs, cb_ = acc[ai][0][m][1] * rs;
;                 f32x4 aa = w2a * ca + ba, ab = w2b * cb_ + bb;
; #pragma unroll
;                 for (int c = 0; c < 4; ++c) { aa[c] = __builtin_fmaf(w1a[c], dpp_shr1(ca[c]), aa[c]); ab[c] = __builtin_fmaf(w1b[c], dpp_shr1(cb_[c]), ab[c]);
;                     aa[c] = __builtin_fmaf(w0a[c], dpp_shr2(ca[c]), aa[c]); ab[c] = __builtin_fmaf(w0b[c], dpp_shr2(cb_[c]), ab[c]); }
;                 if (m == 0) {
;                     if (ai == 1 || wr == 1) { const int sw = ((ai == 1 && wr == 0) ? 4 : 0) + wc, sai = (ai == 1 && wr == 1) ? 1 : 0;
;                         const PG8_LAS f32x4* xp = (const PG8_LAS f32x4*)(X + ((sw * 2 + sai) * 2) * 32 + fq * 8); const f32x4 h0a = xp[0], h0b = xp[1], h1a = xp[8], h1b = xp[9];
;                         aa += w1a * (h1a * m0) + w0a * (h0a * m0 + h1a * m1); ab += w1b * (h1b * m0) + w0b * (h0b * m0 + h1b * m1); }
;                 } else {
; #pragma unroll
;                     for (int c = 0; c < 4; ++c) { aa[c] = __builtin_fmaf(w1a[c], dpp_shl15(pa[c]), aa[c]); ab[c] = __builtin_fmaf(w1b[c], dpp_shl15(pb[c]), ab[c]);
;                         aa[c] = __builtin_fmaf(w0a[c], dpp_shl14(pa[c]), aa[c]); ab[c] = __builtin_fmaf(w0b[c], dpp_shl14(pb[c]), ab[c]); }
;                 }
;                 const f32x4 ga = acc[ai][1][m][0] * rs, gb = acc[ai][1][m][1] * rs;
;                 f32x4 ea = aa * -1.4426950408889634f, eb = ab * -1.4426950408889634f;
; #pragma unroll
;                 for (int c = 0; c < 4; ++c) { ea[c] = __builtin_amdgcn_exp2f(ea[c]); eb[c] = __builtin_amdgcn_exp2f(eb[c]); }
;                 ea = ea + 1.0f; eb = eb + 1.0f;
; #pragma unroll
;                 for (int c = 0; c < 4; ++c) { ea[c] = __builtin_amdgcn_rcpf(ea[c]); eb[c] = __builtin_amdgcn_rcpf(eb[c]); }
;                 const f32x4 oa = (aa * ga) * ea, ob = (ab * gb) * eb;
;                 u32x4 w; w.x = cvt_pk_bf16(oa[0], oa[1]); w.y = cvt_pk_bf16(oa[2], oa[3]); w.z = cvt_pk_bf16(ob[0], ob[1]); w.w = cvt_pk_bf16(ob[2], ob[3]);
;                 *(u32x4*)(act + (size_t)row * FF + col) = w;
	v_cvt_pk_bf16_f32 v217, v238, v239
	v_cvt_pk_bf16_f32 v218, v240, v241
	v_cvt_pk_bf16_f32 v219, v242, v243
	global_store_dwordx4 v[220:221], v[216:219], off nt
	v_lshl_add_u64 v[220:221], v[220:221], 0, s[100:101]
	v_pk_fma_f32 v[236:237], v[122:123], v[78:79], v[130:131]
	v_pk_fma_f32 v[238:239], v[124:125], v[80:81], v[132:133]
	v_pk_fma_f32 v[240:241], v[126:127], v[74:75], v[134:135]
	v_pk_fma_f32 v[242:243], v[128:129], v[76:77], v[136:137]
	v_pk_mul_f32 v[70:71], v[70:71], v[168:169] op_sel_hi:[1,0]
	v_pk_mul_f32 v[72:73], v[72:73], v[168:169] op_sel_hi:[1,0]
	v_pk_mul_f32 v[66:67], v[66:67], v[168:169] op_sel_hi:[1,0]
	v_pk_mul_f32 v[68:69], v[68:69], v[168:169] op_sel_hi:[1,0]
	v_fmac_f32_dpp v236, v78, v114 row_shr:1 row_mask:0xf bank_mask:0xf bound_ctrl:1
	v_fmac_f32_dpp v237, v79, v115 row_shr:1 row_mask:0xf bank_mask:0xf bound_ctrl:1
	v_fmac_f32_dpp v238, v80, v116 row_shr:1 row_mask:0xf bank_mask:0xf bound_ctrl:1
	v_fmac_f32_dpp v239, v81, v117 row_shr:1 row_mask:0xf bank_mask:0xf bound_ctrl:1
	v_fmac_f32_dpp v240, v74, v118 row_shr:1 row_mask:0xf bank_mask:0xf bound_ctrl:1
	v_fmac_f32_dpp v241, v75, v119 row_shr:1 row_mask:0xf bank_mask:0xf bound_ctrl:1
	v_fmac_f32_dpp v242, v76, v120 row_shr:1 row_mask:0xf bank_mask:0xf bound_ctrl:1
	v_fmac_f32_dpp v243, v77, v121 row_shr:1 row_mask:0xf bank_mask:0xf bound_ctrl:1
	v_fmac_f32_dpp v236, v78, v106 row_shr:2 row_mask:0xf bank_mask:0xf bound_ctrl:1
	v_fmac_f32_dpp v237, v79, v107 row_shr:2 row_mask:0xf bank_mask:0xf bound_ctrl:1
	v_fmac_f32_dpp v238, v80, v108 row_shr:2 row_mask:0xf bank_mask:0xf bound_ctrl:1
	v_fmac_f32_dpp v239, v81, v109 row_shr:2 row_mask:0xf bank_mask:0xf bound_ctrl:1
	v_fmac_f32_dpp v240, v74, v110 row_shr:2 row_mask:0xf bank_mask:0xf bound_ctrl:1
	v_fmac_f32_dpp v241, v75, v111 row_shr:2 row_mask:0xf bank_mask:0xf bound_ctrl:1
	v_fmac_f32_dpp v242, v76, v112 row_shr:2 row_mask:0xf bank_mask:0xf bound_ctrl:1
	v_fmac_f32_dpp v243, v77, v113 row_shr:2 row_mask:0xf bank_mask:0xf bound_ctrl:1
	v_fmac_f32_dpp v236, v94, v114 row_shl:15 row_mask:0xf bank_mask:0xf bound_ctrl:1
	v_fmac_f32_dpp v237, v95, v115 row_shl:15 row_mask:0xf bank_mask:0xf bound_ctrl:1
	v_fmac_f32_dpp v238, v96, v116 row_shl:15 row_mask:0xf bank_mask:0xf bound_ctrl:1
	v_fmac_f32_dpp v239, v97, v117 row_shl:15 row_mask:0xf bank_mask:0xf bound_ctrl:1
	v_fmac_f32_dpp v240, v90, v118 row_shl:15 row_mask:0xf bank_mask:0xf bound_ctrl:1
	v_fmac_f32_dpp v241, v91, v119 row_shl:15 row_mask:0xf bank_mask:0xf bound_ctrl:1
	v_fmac_f32_dpp v242, v92, v120 row_shl:15 row_mask:0xf bank_mask:0xf bound_ctrl:1
	v_fmac_f32_dpp v243, v93, v121 row_shl:15 row_mask:0xf bank_mask:0xf bound_ctrl:1
	v_fmac_f32_dpp v236, v94, v106 row_shl:14 row_mask:0xf bank_mask:0xf bound_ctrl:1
	v_fmac_f32_dpp v237, v95, v107 row_shl:14 row_mask:0xf bank_mask:0xf bound_ctrl:1
	v_fmac_f32_dpp v238, v96, v108 row_shl:14 row_mask:0xf bank_mask:0xf bound_ctrl:1
	v_fmac_f32_dpp v239, v97, v109 row_shl:14 row_mask:0xf bank_mask:0xf bound_ctrl:1
	v_fmac_f32_dpp v240, v90, v110 row_shl:14 row_mask:0xf bank_mask:0xf bound_ctrl:1
	v_fmac_f32_dpp v241, v91, v111 row_shl:14 row_mask:0xf bank_mask:0xf bound_ctrl:1
	v_fmac_f32_dpp v242, v92, v112 row_shl:14 row_mask:0xf bank_mask:0xf bound_ctrl:1
	v_fmac_f32_dpp v243, v93, v113 row_shl:14 row_mask:0xf bank_mask:0xf bound_ctrl:1
	v_pk_mul_f32 v[244:245], v[236:237], s[92:93] op_sel_hi:[1,0]
	v_pk_mul_f32 v[246:247], v[238:239], s[92:93] op_sel_hi:[1,0]
	v_pk_mul_f32 v[248:249], v[240:241], s[92:93] op_sel_hi:[1,0]
	v_pk_mul_f32 v[250:251], v[242:243], s[92:93] op_sel_hi:[1,0]
	v_exp_f32_e32 v244, v244
	v_exp_f32_e32 v245, v245
	v_exp_f32_e32 v246, v246
	v_exp_f32_e32 v247, v247
	v_exp_f32_e32 v248, v248
	v_exp_f32_e32 v249, v249
	v_exp_f32_e32 v250, v250
	v_exp_f32_e32 v251, v251
	v_pk_mul_f32 v[236:237], v[236:237], v[70:71]
	v_pk_mul_f32 v[238:239], v[238:239], v[72:73]
	v_pk_mul_f32 v[240:241], v[240:241], v[66:67]
	v_pk_mul_f32 v[242:243], v[242:243], v[68:69]
	v_pk_add_f32 v[244:245], v[244:245], 1.0 op_sel_hi:[1,0]
	v_pk_add_f32 v[246:247], v[246:247], 1.0 op_sel_hi:[1,0]
	v_pk_add_f32 v[248:249], v[248:249], 1.0 op_sel_hi:[1,0]
	v_pk_add_f32 v[250:251], v[250:251], 1.0 op_sel_hi:[1,0]
	v_rcp_f32_e32 v244, v244
	v_rcp_f32_e32 v245, v245
	v_rcp_f32_e32 v246, v246
	v_rcp_f32_e32 v247, v247
	v_rcp_f32_e32 v248, v248
	v_rcp_f32_e32 v249, v249
	v_rcp_f32_e32 v250, v250
	v_rcp_f32_e32 v251, v251
	s_nop 0
	v_pk_mul_f32 v[236:237], v[236:237], v[244:245]
	v_pk_mul_f32 v[238:239], v[238:239], v[246:247]
	v_pk_mul_f32 v[240:241], v[240:241], v[248:249]
	v_pk_mul_f32 v[242:243], v[242:243], v[250:251]
	v_cvt_pk_bf16_f32 v216, v236, v237
	v_cvt_pk_bf16_f32 v217, v238, v239
	v_cvt_pk_bf16_f32 v218, v240, v241
	v_cvt_pk_bf16_f32 v219, v242, v243
	global_store_dwordx4 v[220:221], v[216:219], off nt
	v_lshl_add_u64 v[220:221], v[220:221], 0, s[98:99]
	v_pk_mul_f32 v[62:63], v[62:63], v[170:171] op_sel_hi:[1,0]
	v_pk_mul_f32 v[64:65], v[64:65], v[170:171] op_sel_hi:[1,0]
	v_pk_mul_f32 v[58:59], v[58:59], v[170:171] op_sel_hi:[1,0]
	v_pk_mul_f32 v[60:61], v[60:61], v[170:171] op_sel_hi:[1,0]
	v_lshl_add_u32 v167, v163, 2, s64
	ds_read_b128 v[192:195], v167
	ds_read_b128 v[196:199], v167 offset:16
	ds_read_b128 v[200:203], v167 offset:128
	ds_read_b128 v[204:207], v167 offset:144
	v_pk_fma_f32 v[236:237], v[122:123], v[62:63], v[130:131]
	v_pk_fma_f32 v[238:239], v[124:125], v[64:65], v[132:133]
	v_pk_fma_f32 v[240:241], v[126:127], v[58:59], v[134:135]
	v_pk_fma_f32 v[242:243], v[128:129], v[60:61], v[136:137]
	v_pk_mul_f32 v[54:55], v[54:55], v[170:171] op_sel_hi:[1,0]
	v_pk_mul_f32 v[56:57], v[56:57], v[170:171] op_sel_hi:[1,0]
;     __device__ __forceinline__ void operator()(const f32x4 (&acc)[2][2][4][2], const Unit& u, int wr, int wc, int fr, int fq) const {
;     ...
;             for (int m = 0; m < 4; ++m) {
;                 const int row = row0 + ai * HALF + m * 16; const float rs = rsv[m];
;                 const f32x4 ca = acc[ai][0][m][0] * rs, cb_ = acc[ai][0][m][1] * rs;
;                 f32x4 aa = w2a * ca + ba, ab = w2b * cb_ + bb;
; #pragma unroll
;                 for (int c = 0; c < 4; ++c) { aa[c] = __builtin_fmaf(w1a[c], dpp_shr1(ca[c]), aa[c]); ab[c] = __builtin_fmaf(w1b[c], dpp_shr1(cb_[c]), ab[c]);
;                     aa[c] = __builtin_fmaf(w0a[c], dpp_shr2(ca[c]), aa[c]); ab[c] = __builtin_fmaf(w0b[c], dpp_shr2(cb_[c]), ab[c]); }
;                 if (m == 0) {
;                     if (ai == 1 || wr == 1) { const int sw = ((ai == 1 && wr == 0) ? 4 : 0) + wc, sai = (ai == 1 && wr == 1) ? 1 : 0;
;                         const PG8_LAS f32x4* xp = (const PG8_LAS f32x4*)(X + ((sw * 2 + sai) * 2) * 32 + fq * 8); const f32x4 h0a = xp[0], h0b = xp[1], h1a = xp[8], h1b = xp[9];
;                         aa += w1a * (h1a * m0) + w0a * (h0a * m0 + h1a * m1); ab += w1b * (h1b * m0) + w0b * (h0b * m0 + h1b * m1); }
;                 } else {
; #pragma unroll
;                     for (int c = 0; c < 4; ++c) { aa[c] = __builtin_fmaf(w1a[c], dpp_shl15(pa[c]), aa[c]); ab[c] = __builtin_fmaf(w1b[c], dpp_shl15(pb[c]), ab[c]);
;                         aa[c] = __builtin_fmaf(w0a[c], dpp_shl14(pa[c]), aa[c]); ab[c] = __builtin_fmaf(w0b[c], dpp_shl14(pb[c]), ab[c]); }
;                 }
;                 const f32x4 ga = acc[ai][1][m][0] * rs, gb = acc[ai][1][m][1] * rs;
;                 f32x4 ea = aa * -1.4426950408889634f, eb = ab * -1.4426950408889634f;
; #pragma unroll
;                 for (int c = 0; c < 4; ++c) { ea[c] = __builtin_amdgcn_exp2f(ea[c]); eb[c] = __builtin_amdgcn_exp2f(eb[c]); }
;                 ea = ea + 1.0f; eb = eb + 1.0f;
; #pragma unroll
;                 for (int c = 0; c < 4; ++c) { ea[c] = __builtin_amdgcn_rcpf(ea[c]); eb[c] = __builtin_amdgcn_rcpf(eb[c]); }
;                 const f32x4 oa = (aa * ga) * ea, ob = (ab * gb) * eb;
;                 u32x4 w; w.x = cvt_pk_bf16(oa[0], oa[1]); w.y = cvt_pk_bf16(oa[2], oa[3]); w.z = cvt_pk_bf16(ob[0], ob[1]); w.w = cvt_pk_bf16(ob[2], ob[3]);
;                 *(u32x4*)(act + (size_t)row * FF + col) = w;
	v_pk_mul_f32 v[50:51], v[50:51], v[170:171] op_sel_hi:[1,0]
	v_pk_mul_f32 v[52:53], v[52:53], v[170:171] op_sel_hi:[1,0]
	v_fmac_f32_dpp v236, v62, v114 row_shr:1 row_mask:0xf bank_mask:0xf bound_ctrl:1
	v_fmac_f32_dpp v237, v63, v115 row_shr:1 row_mask:0xf bank_mask:0xf bound_ctrl:1
	v_fmac_f32_dpp v238, v64, v116 row_shr:1 row_mask:0xf bank_mask:0xf bound_ctrl:1
	v_fmac_f32_dpp v239, v65, v117 row_shr:1 row_mask:0xf bank_mask:0xf bound_ctrl:1
	v_fmac_f32_dpp v240, v58, v118 row_shr:1 row_mask:0xf bank_mask:0xf bound_ctrl:1
	v_fmac_f32_dpp v241, v59, v119 row_shr:1 row_mask:0xf bank_mask:0xf bound_ctrl:1
	v_fmac_f32_dpp v242, v60, v120 row_shr:1 row_mask:0xf bank_mask:0xf bound_ctrl:1
	v_fmac_f32_dpp v243, v61, v121 row_shr:1 row_mask:0xf bank_mask:0xf bound_ctrl:1
	v_fmac_f32_dpp v236, v62, v106 row_shr:2 row_mask:0xf bank_mask:0xf bound_ctrl:1
	v_fmac_f32_dpp v237, v63, v107 row_shr:2 row_mask:0xf bank_mask:0xf bound_ctrl:1
	v_fmac_f32_dpp v238, v64, v108 row_shr:2 row_mask:0xf bank_mask:0xf bound_ctrl:1
	v_fmac_f32_dpp v239, v65, v109 row_shr:2 row_mask:0xf bank_mask:0xf bound_ctrl:1
	v_fmac_f32_dpp v240, v58, v110 row_shr:2 row_mask:0xf bank_mask:0xf bound_ctrl:1
	v_fmac_f32_dpp v241, v59, v111 row_shr:2 row_mask:0xf bank_mask:0xf bound_ctrl:1
	v_fmac_f32_dpp v242, v60, v112 row_shr:2 row_mask:0xf bank_mask:0xf bound_ctrl:1
	v_fmac_f32_dpp v243, v61, v113 row_shr:2 row_mask:0xf bank_mask:0xf bound_ctrl:1
	v_cmp_eq_u32_e64 s[44:45], 0, v1
	v_cmp_eq_u32_e64 s[46:47], 1, v1
	s_waitcnt lgkmcnt(0)
	s_mov_b64 exec, s[44:45]
	v_pk_fma_f32 v[236:237], v[114:115], v[200:201], v[236:237]
	v_pk_fma_f32 v[238:239], v[116:117], v[202:203], v[238:239]
	v_pk_fma_f32 v[240:241], v[118:119], v[204:205], v[240:241]
	v_pk_fma_f32 v[242:243], v[120:121], v[206:207], v[242:243]
	v_pk_fma_f32 v[236:237], v[106:107], v[192:193], v[236:237]
	v_pk_fma_f32 v[238:239], v[108:109], v[194:195], v[238:239]
	v_pk_fma_f32 v[240:241], v[110:111], v[196:197], v[240:241]
	v_pk_fma_f32 v[242:243], v[112:113], v[198:199], v[242:243]
	s_mov_b64 exec, s[46:47]
	v_pk_fma_f32 v[236:237], v[106:107], v[200:201], v[236:237]
	v_pk_fma_f32 v[238:239], v[108:109], v[202:203], v[238:239]
	v_pk_fma_f32 v[240:241], v[110:111], v[204:205], v[240:241]
	v_pk_fma_f32 v[242:243], v[112:113], v[206:207], v[242:243]
	s_mov_b64 exec, -1
	v_pk_mul_f32 v[244:245], v[236:237], s[92:93] op_sel_hi:[1,0]
	v_pk_mul_f32 v[246:247], v[238:239], s[92:93] op_sel_hi:[1,0]
	v_pk_mul_f32 v[248:249], v[240:241], s[92:93] op_sel_hi:[1,0]
	v_pk_mul_f32 v[250:251], v[242:243], s[92:93] op_sel_hi:[1,0]
	v_exp_f32_e32 v244, v244
	v_exp_f32_e32 v245, v245
	v_exp_f32_e32 v246, v246
	v_exp_f32_e32 v247, v247
	v_exp_f32_e32 v248, v248
	v_exp_f32_e32 v249, v249
	v_exp_f32_e32 v250, v250
	v_exp_f32_e32 v251, v251
	v_pk_mul_f32 v[236:237], v[236:237], v[54:55]
	v_pk_mul_f32 v[238:239], v[238:239], v[56:57]
	v_pk_mul_f32 v[240:241], v[240:241], v[50:51]
	v_pk_mul_f32 v[242:243], v[242:243], v[52:53]
	v_pk_add_f32 v[244:245], v[244:245], 1.0 op_sel_hi:[1,0]
	v_pk_add_f32 v[246:247], v[246:247], 1.0 op_sel_hi:[1,0]
	v_pk_add_f32 v[248:249], v[248:249], 1.0 op_sel_hi:[1,0]
	v_pk_add_f32 v[250:251], v[250:251], 1.0 op_sel_hi:[1,0]
	v_rcp_f32_e32 v244, v244
	v_rcp_f32_e32 v245, v245
	v_rcp_f32_e32 v246, v246
	v_rcp_f32_e32 v247, v247
	v_rcp_f32_e32 v248, v248
	v_rcp_f32_e32 v249, v249
	v_rcp_f32_e32 v250, v250
	v_rcp_f32_e32 v251, v251
	s_nop 0
	v_pk_mul_f32 v[236:237], v[236:237], v[244:245]
	v_pk_mul_f32 v[238:239], v[238:239], v[246:247]
	v_pk_mul_f32 v[240:241], v[240:241], v[248:249]
	v_pk_mul_f32 v[242:243], v[242:243], v[250:251]
	v_cvt_pk_bf16_f32 v216, v236, v237
	v_cvt_pk_bf16_f32 v217, v238, v239
	v_cvt_pk_bf16_f32 v218, v240, v241
	v_cvt_pk_bf16_f32 v219, v242, v243
	global_store_dwordx4 v[220:221], v[216:219], off nt
	v_lshl_add_u64 v[220:221], v[220:221], 0, s[100:101]
	v_pk_mul_f32 v[46:47], v[46:47], v[172:173] op_sel_hi:[1,0]
	v_pk_mul_f32 v[48:49], v[48:49], v[172:173] op_sel_hi:[1,0]
	v_pk_mul_f32 v[42:43], v[42:43], v[172:173] op_sel_hi:[1,0]
	v_pk_mul_f32 v[44:45], v[44:45], v[172:173] op_sel_hi:[1,0]
	v_pk_fma_f32 v[236:237], v[122:123], v[46:47], v[130:131]
	v_pk_fma_f32 v[238:239], v[124:125], v[48:49], v[132:133]
	v_pk_fma_f32 v[240:241], v[126:127], v[42:43], v[134:135]
	v_pk_fma_f32 v[242:243], v[128:129], v[44:45], v[136:137]
	v_pk_mul_f32 v[38:39], v[38:39], v[172:173] op_sel_hi:[1,0]
	v_pk_mul_f32 v[40:41], v[40:41], v[172:173] op_sel_hi:[1,0]
	v_pk_mul_f32 v[34:35], v[34:35], v[172:173] op_sel_hi:[1,0]
	v_pk_mul_f32 v[36:37], v[36:37], v[172:173] op_sel_hi:[1,0]
	v_fmac_f32_dpp v236, v46, v114 row_shr:1 row_mask:0xf bank_mask:0xf bound_ctrl:1
	v_fmac_f32_dpp v237, v47, v115 row_shr:1 row_mask:0xf bank_mask:0xf bound_ctrl:1
	v_fmac_f32_dpp v238, v48, v116 row_shr:1 row_mask:0xf bank_mask:0xf bound_ctrl:1
	v_fmac_f32_dpp v239, v49, v117 row_shr:1 row_mask:0xf bank_mask:0xf bound_ctrl:1
	v_fmac_f32_dpp v240, v42, v118 row_shr:1 row_mask:0xf bank_mask:0xf bound_ctrl:1
	v_fmac_f32_dpp v241, v43, v119 row_shr:1 row_mask:0xf bank_mask:0xf bound_ctrl:1
	v_fmac_f32_dpp v242, v44, v120 row_shr:1 row_mask:0xf bank_mask:0xf bound_ctrl:1
	v_fmac_f32_dpp v243, v45, v121 row_shr:1 row_mask:0xf bank_mask:0xf bound_ctrl:1
	v_fmac_f32_dpp v236, v46, v106 row_shr:2 row_mask:0xf bank_mask:0xf bound_ctrl:1
	v_fmac_f32_dpp v237, v47, v107 row_shr:2 row_mask:0xf bank_mask:0xf bound_ctrl:1
	v_fmac_f32_dpp v238, v48, v108 row_shr:2 row_mask:0xf bank_mask:0xf bound_ctrl:1
	v_fmac_f32_dpp v239, v49, v109 row_shr:2 row_mask:0xf bank_mask:0xf bound_ctrl:1
	v_fmac_f32_dpp v240, v42, v110 row_shr:2 row_mask:0xf bank_mask:0xf bound_ctrl:1
;     __device__ __forceinline__ void operator()(const f32x4 (&acc)[2][2][4][2], const Unit& u, int wr, int wc, int fr, int fq) const {
;     ...
;             for (int m = 0; m < 4; ++m) {
;                 const int row = row0 + ai * HALF + m * 16; const float rs = rsv[m];
;                 const f32x4 ca = acc[ai][0][m][0] * rs, cb_ = acc[ai][0][m][1] * rs;
;                 f32x4 aa = w2a * ca + ba, ab = w2b * cb_ + bb;
; #pragma unroll
;                 for (int c = 0; c < 4; ++c) { aa[c] = __builtin_fmaf(w1a[c], dpp_shr1(ca[c]), aa[c]); ab[c] = __builtin_fmaf(w1b[c], dpp_shr1(cb_[c]), ab[c]);
;                     aa[c] = __builtin_fmaf(w0a[c], dpp_shr2(ca[c]), aa[c]); ab[c] = __builtin_fmaf(w0b[c], dpp_shr2(cb_[c]), ab[c]); }
;                 if (m == 0) {
;                     if (ai == 1 || wr == 1) { const int sw = ((ai == 1 && wr == 0) ? 4 : 0) + wc, sai = (ai == 1 && wr == 1) ? 1 : 0;
;                         const PG8_LAS f32x4* xp = (const PG8_LAS f32x4*)(X + ((sw * 2 + sai) * 2) * 32 + fq * 8); const f32x4 h0a = xp[0], h0b = xp[1], h1a = xp[8], h1b = xp[9];
;                         aa += w1a * (h1a * m0) + w0a * (h0a * m0 + h1a * m1); ab += w1b * (h1b * m0) + w0b * (h0b * m0 + h1b * m1); }
;                 } else {
; #pragma unroll
;                     for (int c = 0; c < 4; ++c) { aa[c] = __builtin_fmaf(w1a[c], dpp_shl15(pa[c]), aa[c]); ab[c] = __builtin_fmaf(w1b[c], dpp_shl15(pb[c]), ab[c]);
;                         aa[c] = __builtin_fmaf(w0a[c], dpp_shl14(pa[c]), aa[c]); ab[c] = __builtin_fmaf(w0b[c], dpp_shl14(pb[c]), ab[c]); }
;                 }
;                 const f32x4 ga = acc[ai][1][m][0] * rs, gb = acc[ai][1][m][1] * rs;
;                 f32x4 ea = aa * -1.4426950408889634f, eb = ab * -1.4426950408889634f;
; #pragma unroll
;                 for (int c = 0; c < 4; ++c) { ea[c] = __builtin_amdgcn_exp2f(ea[c]); eb[c] = __builtin_amdgcn_exp2f(eb[c]); }
;                 ea = ea + 1.0f; eb = eb + 1.0f;
; #pragma unroll
;                 for (int c = 0; c < 4; ++c) { ea[c] = __builtin_amdgcn_rcpf(ea[c]); eb[c] = __builtin_amdgcn_rcpf(eb[c]); }
;                 const f32x4 oa = (aa * ga) * ea, ob = (ab * gb) * eb;
;                 u32x4 w; w.x = cvt_pk_bf16(oa[0], oa[1]); w.y = cvt_pk_bf16(oa[2], oa[3]); w.z = cvt_pk_bf16(ob[0], ob[1]); w.w = cvt_pk_bf16(ob[2], ob[3]);
;                 *(u32x4*)(act + (size_t)row * FF + col) = w;
	v_fmac_f32_dpp v241, v43, v111 row_shr:2 row_mask:0xf bank_mask:0xf bound_ctrl:1
	v_fmac_f32_dpp v242, v44, v112 row_shr:2 row_mask:0xf bank_mask:0xf bound_ctrl:1
	v_fmac_f32_dpp v243, v45, v113 row_shr:2 row_mask:0xf bank_mask:0xf bound_ctrl:1
	v_fmac_f32_dpp v236, v62, v114 row_shl:15 row_mask:0xf bank_mask:0xf bound_ctrl:1
	v_fmac_f32_dpp v237, v63, v115 row_shl:15 row_mask:0xf bank_mask:0xf bound_ctrl:1
	v_fmac_f32_dpp v238, v64, v116 row_shl:15 row_mask:0xf bank_mask:0xf bound_ctrl:1
	v_fmac_f32_dpp v239, v65, v117 row_shl:15 row_mask:0xf bank_mask:0xf bound_ctrl:1
	v_fmac_f32_dpp v240, v58, v118 row_shl:15 row_mask:0xf bank_mask:0xf bound_ctrl:1
	v_fmac_f32_dpp v241, v59, v119 row_shl:15 row_mask:0xf bank_mask:0xf bound_ctrl:1
	v_fmac_f32_dpp v242, v60, v120 row_shl:15 row_mask:0xf bank_mask:0xf bound_ctrl:1
	v_fmac_f32_dpp v243, v61, v121 row_shl:15 row_mask:0xf bank_mask:0xf bound_ctrl:1
	v_fmac_f32_dpp v236, v62, v106 row_shl:14 row_mask:0xf bank_mask:0xf bound_ctrl:1
	v_fmac_f32_dpp v237, v63, v107 row_shl:14 row_mask:0xf bank_mask:0xf bound_ctrl:1
	v_fmac_f32_dpp v238, v64, v108 row_shl:14 row_mask:0xf bank_mask:0xf bound_ctrl:1
	v_fmac_f32_dpp v239, v65, v109 row_shl:14 row_mask:0xf bank_mask:0xf bound_ctrl:1
	v_fmac_f32_dpp v240, v58, v110 row_shl:14 row_mask:0xf bank_mask:0xf bound_ctrl:1
	v_fmac_f32_dpp v241, v59, v111 row_shl:14 row_mask:0xf bank_mask:0xf bound_ctrl:1
	v_fmac_f32_dpp v242, v60, v112 row_shl:14 row_mask:0xf bank_mask:0xf bound_ctrl:1
	v_fmac_f32_dpp v243, v61, v113 row_shl:14 row_mask:0xf bank_mask:0xf bound_ctrl:1
	v_pk_mul_f32 v[244:245], v[236:237], s[92:93] op_sel_hi:[1,0]
	v_pk_mul_f32 v[246:247], v[238:239], s[92:93] op_sel_hi:[1,0]
	v_pk_mul_f32 v[248:249], v[240:241], s[92:93] op_sel_hi:[1,0]
	v_pk_mul_f32 v[250:251], v[242:243], s[92:93] op_sel_hi:[1,0]
	v_exp_f32_e32 v244, v244
	v_exp_f32_e32 v245, v245
	v_exp_f32_e32 v246, v246
	v_exp_f32_e32 v247, v247
	v_exp_f32_e32 v248, v248
	v_exp_f32_e32 v249, v249
	v_exp_f32_e32 v250, v250
	v_exp_f32_e32 v251, v251
	v_pk_mul_f32 v[236:237], v[236:237], v[38:39]
	v_pk_mul_f32 v[238:239], v[238:239], v[40:41]
	v_pk_mul_f32 v[240:241], v[240:241], v[34:35]
	v_pk_mul_f32 v[242:243], v[242:243], v[36:37]
	v_pk_add_f32 v[244:245], v[244:245], 1.0 op_sel_hi:[1,0]
	v_pk_add_f32 v[246:247], v[246:247], 1.0 op_sel_hi:[1,0]
	v_pk_add_f32 v[248:249], v[248:249], 1.0 op_sel_hi:[1,0]
	v_pk_add_f32 v[250:251], v[250:251], 1.0 op_sel_hi:[1,0]
	v_rcp_f32_e32 v244, v244
	v_rcp_f32_e32 v245, v245
	v_rcp_f32_e32 v246, v246
	v_rcp_f32_e32 v247, v247
	v_rcp_f32_e32 v248, v248
	v_rcp_f32_e32 v249, v249
	v_rcp_f32_e32 v250, v250
	v_rcp_f32_e32 v251, v251
	s_nop 0
	v_pk_mul_f32 v[236:237], v[236:237], v[244:245]
	v_pk_mul_f32 v[238:239], v[238:239], v[246:247]
	v_pk_mul_f32 v[240:241], v[240:241], v[248:249]
	v_pk_mul_f32 v[242:243], v[242:243], v[250:251]
	v_cvt_pk_bf16_f32 v216, v236, v237
	v_cvt_pk_bf16_f32 v217, v238, v239
	v_cvt_pk_bf16_f32 v218, v240, v241
	v_cvt_pk_bf16_f32 v219, v242, v243
	global_store_dwordx4 v[220:221], v[216:219], off nt
	v_lshl_add_u64 v[220:221], v[220:221], 0, s[100:101]
	v_pk_mul_f32 v[30:31], v[30:31], v[232:233] op_sel_hi:[1,0]
	v_pk_mul_f32 v[32:33], v[32:33], v[232:233] op_sel_hi:[1,0]
	v_pk_mul_f32 v[26:27], v[26:27], v[232:233] op_sel_hi:[1,0]
	v_pk_mul_f32 v[28:29], v[28:29], v[232:233] op_sel_hi:[1,0]
	v_pk_fma_f32 v[236:237], v[122:123], v[30:31], v[130:131]
	v_pk_fma_f32 v[238:239], v[124:125], v[32:33], v[132:133]
	v_pk_fma_f32 v[240:241], v[126:127], v[26:27], v[134:135]
	v_pk_fma_f32 v[242:243], v[128:129], v[28:29], v[136:137]
	v_pk_mul_f32 v[22:23], v[22:23], v[232:233] op_sel_hi:[1,0]
	v_pk_mul_f32 v[24:25], v[24:25], v[232:233] op_sel_hi:[1,0]
	v_pk_mul_f32 v[18:19], v[18:19], v[232:233] op_sel_hi:[1,0]
	v_pk_mul_f32 v[20:21], v[20:21], v[232:233] op_sel_hi:[1,0]
	v_fmac_f32_dpp v236, v30, v114 row_shr:1 row_mask:0xf bank_mask:0xf bound_ctrl:1
	v_fmac_f32_dpp v237, v31, v115 row_shr:1 row_mask:0xf bank_mask:0xf bound_ctrl:1
	v_fmac_f32_dpp v238, v32, v116 row_shr:1 row_mask:0xf bank_mask:0xf bound_ctrl:1
	v_fmac_f32_dpp v239, v33, v117 row_shr:1 row_mask:0xf bank_mask:0xf bound_ctrl:1
	v_fmac_f32_dpp v240, v26, v118 row_shr:1 row_mask:0xf bank_mask:0xf bound_ctrl:1
	v_fmac_f32_dpp v241, v27, v119 row_shr:1 row_mask:0xf bank_mask:0xf bound_ctrl:1
	v_fmac_f32_dpp v242, v28, v120 row_shr:1 row_mask:0xf bank_mask:0xf bound_ctrl:1
	v_fmac_f32_dpp v243, v29, v121 row_shr:1 row_mask:0xf bank_mask:0xf bound_ctrl:1
	v_fmac_f32_dpp v236, v30, v106 row_shr:2 row_mask:0xf bank_mask:0xf bound_ctrl:1
	v_fmac_f32_dpp v237, v31, v107 row_shr:2 row_mask:0xf bank_mask:0xf bound_ctrl:1
	v_fmac_f32_dpp v238, v32, v108 row_shr:2 row_mask:0xf bank_mask:0xf bound_ctrl:1
	v_fmac_f32_dpp v239, v33, v109 row_shr:2 row_mask:0xf bank_mask:0xf bound_ctrl:1
	v_fmac_f32_dpp v240, v26, v110 row_shr:2 row_mask:0xf bank_mask:0xf bound_ctrl:1
	v_fmac_f32_dpp v241, v27, v111 row_shr:2 row_mask:0xf bank_mask:0xf bound_ctrl:1
	v_fmac_f32_dpp v242, v28, v112 row_shr:2 row_mask:0xf bank_mask:0xf bound_ctrl:1
	v_fmac_f32_dpp v243, v29, v113 row_shr:2 row_mask:0xf bank_mask:0xf bound_ctrl:1
	v_fmac_f32_dpp v236, v46, v114 row_shl:15 row_mask:0xf bank_mask:0xf bound_ctrl:1
	v_fmac_f32_dpp v237, v47, v115 row_shl:15 row_mask:0xf bank_mask:0xf bound_ctrl:1
	v_fmac_f32_dpp v238, v48, v116 row_shl:15 row_mask:0xf bank_mask:0xf bound_ctrl:1
	v_fmac_f32_dpp v239, v49, v117 row_shl:15 row_mask:0xf bank_mask:0xf bound_ctrl:1
	v_fmac_f32_dpp v240, v42, v118 row_shl:15 row_mask:0xf bank_mask:0xf bound_ctrl:1
	v_fmac_f32_dpp v241, v43, v119 row_shl:15 row_mask:0xf bank_mask:0xf bound_ctrl:1
;     __device__ __forceinline__ void operator()(const f32x4 (&acc)[2][2][4][2], const Unit& u, int wr, int wc, int fr, int fq) const {
;     ...
;             for (int m = 0; m < 4; ++m) {
;                 const int row = row0 + ai * HALF + m * 16; const float rs = rsv[m];
;                 const f32x4 ca = acc[ai][0][m][0] * rs, cb_ = acc[ai][0][m][1] * rs;
;                 f32x4 aa = w2a * ca + ba, ab = w2b * cb_ + bb;
; #pragma unroll
;                 for (int c = 0; c < 4; ++c) { aa[c] = __builtin_fmaf(w1a[c], dpp_shr1(ca[c]), aa[c]); ab[c] = __builtin_fmaf(w1b[c], dpp_shr1(cb_[c]), ab[c]);
;                     aa[c] = __builtin_fmaf(w0a[c], dpp_shr2(ca[c]), aa[c]); ab[c] = __builtin_fmaf(w0b[c], dpp_shr2(cb_[c]), ab[c]); }
;                 if (m == 0) {
;                     if (ai == 1 || wr == 1) { const int sw = ((ai == 1 && wr == 0) ? 4 : 0) + wc, sai = (ai == 1 && wr == 1) ? 1 : 0;
;                         const PG8_LAS f32x4* xp = (const PG8_LAS f32x4*)(X + ((sw * 2 + sai) * 2) * 32 + fq * 8); const f32x4 h0a = xp[0], h0b = xp[1], h1a = xp[8], h1b = xp[9];
;                         aa += w1a * (h1a * m0) + w0a * (h0a * m0 + h1a * m1); ab += w1b * (h1b * m0) + w0b * (h0b * m0 + h1b * m1); }
;                 } else {
; #pragma unroll
;                     for (int c = 0; c < 4; ++c) { aa[c] = __builtin_fmaf(w1a[c], dpp_shl15(pa[c]), aa[c]); ab[c] = __builtin_fmaf(w1b[c], dpp_shl15(pb[c]), ab[c]);
;                         aa[c] = __builtin_fmaf(w0a[c], dpp_shl14(pa[c]), aa[c]); ab[c] = __builtin_fmaf(w0b[c], dpp_shl14(pb[c]), ab[c]); }
;                 }
;                 const f32x4 ga = acc[ai][1][m][0] * rs, gb = acc[ai][1][m][1] * rs;
;                 f32x4 ea = aa * -1.4426950408889634f, eb = ab * -1.4426950408889634f;
; #pragma unroll
;                 for (int c = 0; c < 4; ++c) { ea[c] = __builtin_amdgcn_exp2f(ea[c]); eb[c] = __builtin_amdgcn_exp2f(eb[c]); }
;                 ea = ea + 1.0f; eb = eb + 1.0f;
; #pragma unroll
;                 for (int c = 0; c < 4; ++c) { ea[c] = __builtin_amdgcn_rcpf(ea[c]); eb[c] = __builtin_amdgcn_rcpf(eb[c]); }
;                 const f32x4 oa = (aa * ga) * ea, ob = (ab * gb) * eb;
;                 u32x4 w; w.x = cvt_pk_bf16(oa[0], oa[1]); w.y = cvt_pk_bf16(oa[2], oa[3]); w.z = cvt_pk_bf16(ob[0], ob[1]); w.w = cvt_pk_bf16(ob[2], ob[3]);
;                 *(u32x4*)(act + (size_t)row * FF + col) = w;
	v_fmac_f32_dpp v242, v44, v120 row_shl:15 row_mask:0xf bank_mask:0xf bound_ctrl:1
	v_fmac_f32_dpp v243, v45, v121 row_shl:15 row_mask:0xf bank_mask:0xf bound_ctrl:1
	v_fmac_f32_dpp v236, v46, v106 row_shl:14 row_mask:0xf bank_mask:0xf bound_ctrl:1
	v_fmac_f32_dpp v237, v47, v107 row_shl:14 row_mask:0xf bank_mask:0xf bound_ctrl:1
	v_fmac_f32_dpp v238, v48, v108 row_shl:14 row_mask:0xf bank_mask:0xf bound_ctrl:1
	v_fmac_f32_dpp v239, v49, v109 row_shl:14 row_mask:0xf bank_mask:0xf bound_ctrl:1
	v_fmac_f32_dpp v240, v42, v110 row_shl:14 row_mask:0xf bank_mask:0xf bound_ctrl:1
	v_fmac_f32_dpp v241, v43, v111 row_shl:14 row_mask:0xf bank_mask:0xf bound_ctrl:1
	v_fmac_f32_dpp v242, v44, v112 row_shl:14 row_mask:0xf bank_mask:0xf bound_ctrl:1
	v_fmac_f32_dpp v243, v45, v113 row_shl:14 row_mask:0xf bank_mask:0xf bound_ctrl:1
	v_pk_mul_f32 v[244:245], v[236:237], s[92:93] op_sel_hi:[1,0]
	v_pk_mul_f32 v[246:247], v[238:239], s[92:93] op_sel_hi:[1,0]
	v_pk_mul_f32 v[248:249], v[240:241], s[92:93] op_sel_hi:[1,0]
	v_pk_mul_f32 v[250:251], v[242:243], s[92:93] op_sel_hi:[1,0]
	v_exp_f32_e32 v244, v244
	v_exp_f32_e32 v245, v245
	v_exp_f32_e32 v246, v246
	v_exp_f32_e32 v247, v247
	v_exp_f32_e32 v248, v248
	v_exp_f32_e32 v249, v249
	v_exp_f32_e32 v250, v250
	v_exp_f32_e32 v251, v251
	v_pk_mul_f32 v[236:237], v[236:237], v[22:23]
	v_pk_mul_f32 v[238:239], v[238:239], v[24:25]
	v_pk_mul_f32 v[240:241], v[240:241], v[18:19]
	v_pk_mul_f32 v[242:243], v[242:243], v[20:21]
	v_pk_add_f32 v[244:245], v[244:245], 1.0 op_sel_hi:[1,0]
	v_pk_add_f32 v[246:247], v[246:247], 1.0 op_sel_hi:[1,0]
	v_pk_add_f32 v[248:249], v[248:249], 1.0 op_sel_hi:[1,0]
	v_pk_add_f32 v[250:251], v[250:251], 1.0 op_sel_hi:[1,0]
	v_rcp_f32_e32 v244, v244
	v_rcp_f32_e32 v245, v245
	v_rcp_f32_e32 v246, v246
	v_rcp_f32_e32 v247, v247
	v_rcp_f32_e32 v248, v248
	v_rcp_f32_e32 v249, v249
	v_rcp_f32_e32 v250, v250
	v_rcp_f32_e32 v251, v251
	s_nop 0
	v_pk_mul_f32 v[236:237], v[236:237], v[244:245]
	v_pk_mul_f32 v[238:239], v[238:239], v[246:247]
	v_pk_mul_f32 v[240:241], v[240:241], v[248:249]
	v_pk_mul_f32 v[242:243], v[242:243], v[250:251]
	v_cvt_pk_bf16_f32 v216, v236, v237
	v_cvt_pk_bf16_f32 v217, v238, v239
	v_cvt_pk_bf16_f32 v218, v240, v241
	v_cvt_pk_bf16_f32 v219, v242, v243
	global_store_dwordx4 v[220:221], v[216:219], off nt
	v_lshl_add_u64 v[220:221], v[220:221], 0, s[100:101]
	v_pk_fma_f32 v[236:237], v[122:123], v[14:15], v[130:131]
	v_pk_fma_f32 v[238:239], v[124:125], v[16:17], v[132:133]
	v_pk_fma_f32 v[240:241], v[126:127], v[10:11], v[134:135]
	v_pk_fma_f32 v[242:243], v[128:129], v[12:13], v[136:137]
	v_pk_mul_f32 v[6:7], v[6:7], v[234:235] op_sel_hi:[1,0]
	v_pk_mul_f32 v[8:9], v[8:9], v[234:235] op_sel_hi:[1,0]
	v_pk_mul_f32 v[2:3], v[2:3], v[234:235] op_sel_hi:[1,0]
	v_pk_mul_f32 v[4:5], v[4:5], v[234:235] op_sel_hi:[1,0]
	v_fmac_f32_dpp v236, v14, v114 row_shr:1 row_mask:0xf bank_mask:0xf bound_ctrl:1
	v_fmac_f32_dpp v237, v15, v115 row_shr:1 row_mask:0xf bank_mask:0xf bound_ctrl:1
	v_fmac_f32_dpp v238, v16, v116 row_shr:1 row_mask:0xf bank_mask:0xf bound_ctrl:1
	v_fmac_f32_dpp v239, v17, v117 row_shr:1 row_mask:0xf bank_mask:0xf bound_ctrl:1
	v_fmac_f32_dpp v240, v10, v118 row_shr:1 row_mask:0xf bank_mask:0xf bound_ctrl:1
	v_fmac_f32_dpp v241, v11, v119 row_shr:1 row_mask:0xf bank_mask:0xf bound_ctrl:1
	v_fmac_f32_dpp v242, v12, v120 row_shr:1 row_mask:0xf bank_mask:0xf bound_ctrl:1
	v_fmac_f32_dpp v243, v13, v121 row_shr:1 row_mask:0xf bank_mask:0xf bound_ctrl:1
	v_fmac_f32_dpp v236, v14, v106 row_shr:2 row_mask:0xf bank_mask:0xf bound_ctrl:1
;     __device__ __forceinline__ void operator()(const f32x4 (&acc)[2][2][4][2], const Unit& u, int wr, int wc, int fr, int fq) const {
;     ...
;             for (int m = 0; m < 4; ++m) {
;                 const int row = row0 + ai * HALF + m * 16; const float rs = rsv[m];
;                 const f32x4 ca = acc[ai][0][m][0] * rs, cb_ = acc[ai][0][m][1] * rs;
;                 f32x4 aa = w2a * ca + ba, ab = w2b * cb_ + bb;
; #pragma unroll
;                 for (int c = 0; c < 4; ++c) { aa[c] = __builtin_fmaf(w1a[c], dpp_shr1(ca[c]), aa[c]); ab[c] = __builtin_fmaf(w1b[c], dpp_shr1(cb_[c]), ab[c]);
;                     aa[c] = __builtin_fmaf(w0a[c], dpp_shr2(ca[c]), aa[c]); ab[c] = __builtin_fmaf(w0b[c], dpp_shr2(cb_[c]), ab[c]); }
;                 if (m == 0) {
;                     if (ai == 1 || wr == 1) { const int sw = ((ai == 1 && wr == 0) ? 4 : 0) + wc, sai = (ai == 1 && wr == 1) ? 1 : 0;
;                         const PG8_LAS f32x4* xp = (const PG8_LAS f32x4*)(X + ((sw * 2 + sai) * 2) * 32 + fq * 8); const f32x4 h0a = xp[0], h0b = xp[1], h1a = xp[8], h1b = xp[9];
;                         aa += w1a * (h1a * m0) + w0a * (h0a * m0 + h1a * m1); ab += w1b * (h1b * m0) + w0b * (h0b * m0 + h1b * m1); }
;                 } else {
; #pragma unroll
;                     for (int c = 0; c < 4; ++c) { aa[c] = __builtin_fmaf(w1a[c], dpp_shl15(pa[c]), aa[c]); ab[c] = __builtin_fmaf(w1b[c], dpp_shl15(pb[c]), ab[c]);
;                         aa[c] = __builtin_fmaf(w0a[c], dpp_shl14(pa[c]), aa[c]); ab[c] = __builtin_fmaf(w0b[c], dpp_shl14(pb[c]), ab[c]); }
;                 }
;                 const f32x4 ga = acc[ai][1][m][0] * rs, gb = acc[ai][1][m][1] * rs;
;                 f32x4 ea = aa * -1.4426950408889634f, eb = ab * -1.4426950408889634f;
; #pragma unroll
;                 for (int c = 0; c < 4; ++c) { ea[c] = __builtin_amdgcn_exp2f(ea[c]); eb[c] = __builtin_amdgcn_exp2f(eb[c]); }
;                 ea = ea + 1.0f; eb = eb + 1.0f;
; #pragma unroll
;                 for (int c = 0; c < 4; ++c) { ea[c] = __builtin_amdgcn_rcpf(ea[c]); eb[c] = __builtin_amdgcn_rcpf(eb[c]); }
;                 const f32x4 oa = (aa * ga) * ea, ob = (ab * gb) * eb;
;                 u32x4 w; w.x = cvt_pk_bf16(oa[0], oa[1]); w.y = cvt_pk_bf16(oa[2], oa[3]); w.z = cvt_pk_bf16(ob[0], ob[1]); w.w = cvt_pk_bf16(ob[2], ob[3]);
;                 *(u32x4*)(act + (size_t)row * FF + col) = w;
	v_fmac_f32_dpp v237, v15, v107 row_shr:2 row_mask:0xf bank_mask:0xf bound_ctrl:1
	v_fmac_f32_dpp v238, v16, v108 row_shr:2 row_mask:0xf bank_mask:0xf bound_ctrl:1
	v_fmac_f32_dpp v239, v17, v109 row_shr:2 row_mask:0xf bank_mask:0xf bound_ctrl:1
	v_fmac_f32_dpp v240, v10, v110 row_shr:2 row_mask:0xf bank_mask:0xf bound_ctrl:1
	v_fmac_f32_dpp v241, v11, v111 row_shr:2 row_mask:0xf bank_mask:0xf bound_ctrl:1
	v_fmac_f32_dpp v242, v12, v112 row_shr:2 row_mask:0xf bank_mask:0xf bound_ctrl:1
	v_fmac_f32_dpp v243, v13, v113 row_shr:2 row_mask:0xf bank_mask:0xf bound_ctrl:1
	v_fmac_f32_dpp v236, v30, v114 row_shl:15 row_mask:0xf bank_mask:0xf bound_ctrl:1
	v_fmac_f32_dpp v237, v31, v115 row_shl:15 row_mask:0xf bank_mask:0xf bound_ctrl:1
	v_fmac_f32_dpp v238, v32, v116 row_shl:15 row_mask:0xf bank_mask:0xf bound_ctrl:1
	v_fmac_f32_dpp v239, v33, v117 row_shl:15 row_mask:0xf bank_mask:0xf bound_ctrl:1
	v_fmac_f32_dpp v240, v26, v118 row_shl:15 row_mask:0xf bank_mask:0xf bound_ctrl:1
	v_fmac_f32_dpp v241, v27, v119 row_shl:15 row_mask:0xf bank_mask:0xf bound_ctrl:1
	v_fmac_f32_dpp v242, v28, v120 row_shl:15 row_mask:0xf bank_mask:0xf bound_ctrl:1
	v_fmac_f32_dpp v243, v29, v121 row_shl:15 row_mask:0xf bank_mask:0xf bound_ctrl:1
	v_fmac_f32_dpp v236, v30, v106 row_shl:14 row_mask:0xf bank_mask:0xf bound_ctrl:1
	v_fmac_f32_dpp v237, v31, v107 row_shl:14 row_mask:0xf bank_mask:0xf bound_ctrl:1
	v_fmac_f32_dpp v238, v32, v108 row_shl:14 row_mask:0xf bank_mask:0xf bound_ctrl:1
	v_fmac_f32_dpp v239, v33, v109 row_shl:14 row_mask:0xf bank_mask:0xf bound_ctrl:1
	v_fmac_f32_dpp v240, v26, v110 row_shl:14 row_mask:0xf bank_mask:0xf bound_ctrl:1
	v_fmac_f32_dpp v241, v27, v111 row_shl:14 row_mask:0xf bank_mask:0xf bound_ctrl:1
	v_fmac_f32_dpp v242, v28, v112 row_shl:14 row_mask:0xf bank_mask:0xf bound_ctrl:1
	v_fmac_f32_dpp v243, v29, v113 row_shl:14 row_mask:0xf bank_mask:0xf bound_ctrl:1
	v_pk_mul_f32 v[244:245], v[236:237], s[92:93] op_sel_hi:[1,0]
	v_pk_mul_f32 v[246:247], v[238:239], s[92:93] op_sel_hi:[1,0]
	v_pk_mul_f32 v[248:249], v[240:241], s[92:93] op_sel_hi:[1,0]
	v_pk_mul_f32 v[250:251], v[242:243], s[92:93] op_sel_hi:[1,0]
	v_exp_f32_e32 v244, v244
	v_exp_f32_e32 v245, v245
	v_exp_f32_e32 v246, v246
	v_exp_f32_e32 v247, v247
	v_exp_f32_e32 v248, v248
	v_exp_f32_e32 v249, v249
	v_exp_f32_e32 v250, v250
	v_exp_f32_e32 v251, v251
	v_pk_mul_f32 v[236:237], v[236:237], v[6:7]
	v_pk_mul_f32 v[238:239], v[238:239], v[8:9]
	v_pk_mul_f32 v[240:241], v[240:241], v[2:3]
	v_pk_mul_f32 v[242:243], v[242:243], v[4:5]
	v_pk_add_f32 v[244:245], v[244:245], 1.0 op_sel_hi:[1,0]
	v_pk_add_f32 v[246:247], v[246:247], 1.0 op_sel_hi:[1,0]
	v_pk_add_f32 v[248:249], v[248:249], 1.0 op_sel_hi:[1,0]
	v_pk_add_f32 v[250:251], v[250:251], 1.0 op_sel_hi:[1,0]
	v_rcp_f32_e32 v244, v244
	v_rcp_f32_e32 v245, v245
	v_rcp_f32_e32 v246, v246
	v_rcp_f32_e32 v247, v247
	v_rcp_f32_e32 v248, v248
	v_rcp_f32_e32 v249, v249
	v_rcp_f32_e32 v250, v250
	v_rcp_f32_e32 v251, v251
	s_nop 0
	v_pk_mul_f32 v[236:237], v[236:237], v[244:245]
	v_pk_mul_f32 v[238:239], v[238:239], v[246:247]
	v_pk_mul_f32 v[240:241], v[240:241], v[248:249]
	v_pk_mul_f32 v[242:243], v[242:243], v[250:251]
	v_cvt_pk_bf16_f32 v216, v236, v237
	v_cvt_pk_bf16_f32 v217, v238, v239
	v_cvt_pk_bf16_f32 v218, v240, v241
	v_cvt_pk_bf16_f32 v219, v242, v243
	global_store_dwordx4 v[220:221], v[216:219], off nt
	s_mov_b64 s[66:67], 0x8000
	s_andn2_b64 vcc, exec, s[6:7]
	s_mov_b64 s[6:7], -1
	s_not_b64 s[8:9], s[4:5]
	s_cbranch_vccnz .LBB0_1243
	s_and_b64 vcc, exec, s[8:9]
	s_cbranch_vccnz .LBB0_1242
	s_barrier
	s_branch .LBB0_1242
